# v96 + OUT tail as 256 quarter-M units on all workgroups (was 128 half-M units on half of them)
# speedup vs baseline: 1.0004x; 1.0004x over previous
;     __host__ __device__ bool next(int i, Unit& u) const { if (i != 0 || S.c >= 2 * (S.nwg - base)) return false; S.unit_of(base + (S.c >> 1), u); u.hm = S.c & 1; return true; }
; #define PG8_STAGE(bufoff, gbase) do { _Pragma("unroll") for (int _i = 0; _i < 2; ++_i) \
;         __builtin_amdgcn_global_load_lds((const unsigned*)((const char*)(gbase) + voffA[_i]), (LAS unsigned*)(lds + (bufoff) + ldsw + _i * 8192), 16, 0, 0); } while (0)
; #define PG8_WAIT_V(n) asm volatile("s_waitcnt vmcnt(" #n ")" ::: "memory")
; #define PG8_BAR __builtin_amdgcn_s_barrier()
; template <class Epi, bool ALIGN_EPI, bool SP2, bool BF = false, bool HALFM = false, class Order = StaticOrder>
; __device__ __forceinline__ void gemm_phase(LAS unsigned char* lds, const int tid, const Gemm g, const Order& S, const Epi& E, const bool dry = false) {
;     ...
;     Unit cur, nxt; int ui = 0;
;     if (!S.next(0, cur)) return;
;     f32x4 acc[2][2][4][2];
; #pragma unroll
;     for (int a = 0; a < 2; ++a)
; #pragma unroll
;         for (int b = 0; b < 2; ++b)
; #pragma unroll
;             for (int m = 0; m < 4; ++m)
; #pragma unroll
;                 for (int n = 0; n < 2; ++n) acc[a][b][m][n] = (f32x4){0.f, 0.f, 0.f, 0.f};
;     h16x8 At[4][2], B0[2][2], B1[2][2];
;     const char* cA = (const char*)g.A + (size_t)cur.pm * tstep + (HALFM ? (size_t)cur.hm * hstep : (size_t)0); const char* cB = (const char*)g.Bt + (size_t)cur.pn * tstep;
;     if constexpr (SP2) {
;         PG8_STAGE(PG8_SB(0, 0), cB); PG8_STAGE(PG8_SB(0, 1), cB + hstep); PG8_STAGE(PG8_SA(0, 0), cA); PG8_STAGE(PG8_SA(0, 1), cA + hstep);
;         if (wr == 1) PG8_BAR;
;         PG8_WAIT_V(2); PG8_BAR;
;         PG8_STAGE(PG8_SB(1, 0), cB + kstep); PG8_STAGE(PG8_SA(1, 0), cA + kstep); PG8_STAGE(PG8_SB(1, 1), cB + hstep + kstep);
;         PG8_WAIT_V(6); PG8_BAR;
.LBB0_499:
	s_andn2_b64 vcc, exec, s[14:15]
	s_cbranch_vccnz .LBB0_532
	s_lshl_b32 s11, s11, 1
	s_cmp_ge_i32 s73, s11
	v_readfirstlane_b32 s15, v212
	s_cbranch_scc1 .LBB0_532
	s_ashr_i32 s0, s73, 2
	s_add_i32 s0, s69, s0
	s_ashr_i32 s2, s0, 31
	s_lshr_b32 s2, s2, 29
	s_add_i32 s2, s0, s2
	s_ashr_i32 s3, s2, 3
	s_and_b32 s2, s2, -8
	s_sub_i32 s0, s0, s2
	s_lshr_b32 s1, s47, 1
	s_lshr_b32 s2, s0, 31
	s_or_b32 s1, s2, s1
	s_mul_i32 s0, s1, s0
	s_add_i32 s0, s0, s3
	s_ashr_i32 s1, s0, 31
	s_lshr_b32 s1, s1, 27
	s_add_i32 s1, s0, s1
	s_ashr_i32 s2, s1, 5
	s_lshl_b32 s2, s2, 3
	s_sub_i32 s3, s47, s2
	s_min_i32 s3, s3, 8
	s_abs_i32 s4, s3
	v_cvt_f32_u32_e32 v0, s4
	s_sub_i32 s7, 0, s4
	s_andn2_b32 s1, s1, 31
	s_sub_i32 s0, s0, s1
	v_rcp_iflag_f32_e32 v0, v0
	s_abs_i32 s5, s0
	s_ashr_i32 s36, s15, 6
	s_xor_b32 s1, s0, s3
	v_mul_f32_e32 v0, 0x4f7ffffe, v0
	v_cvt_u32_f32_e32 v0, v0
	s_ashr_i32 s29, s15, 8
	s_lshl_b32 s6, s36, 10
	s_ashr_i32 s1, s1, 31
	v_readfirstlane_b32 s8, v0
	s_mul_i32 s7, s7, s8
	s_mul_hi_u32 s7, s8, s7
	s_add_i32 s8, s8, s7
	s_mul_hi_u32 s7, s5, s8
	s_mul_i32 s8, s7, s4
	s_sub_i32 s5, s5, s8
	s_add_i32 s8, s7, 1
	s_sub_i32 s9, s5, s4
	s_cmp_ge_u32 s5, s4
	s_cselect_b32 s7, s8, s7
	s_cselect_b32 s5, s9, s5
	s_add_i32 s8, s7, 1
	s_cmp_ge_u32 s5, s4
	s_cselect_b32 s4, s8, s7
	s_xor_b32 s4, s4, s1
	s_sub_i32 s4, s4, s1
	s_mul_i32 s1, s4, s3
	s_sub_i32 s0, s0, s1
	s_add_i32 s0, s0, s2
	s_bfe_u32 s14, s73, 0x10001
	s_and_b32 s101, s73, 1
	s_ashr_i32 s1, s0, 31
	s_ashr_i32 s5, s4, 31
	s_lshl_b64 s[12:13], s[0:1], 19
	s_lshl_b32 s7, s14, 18
	s_lshl_b64 s[10:11], s[4:5], 19
	s_add_u32 s2, s49, s10
	s_addc_u32 s3, s50, s11
	s_add_i32 s16, s74, 0x10000
	v_readlane_b32 s56, v251, 0
	s_add_i32 s17, s16, s6
	v_readlane_b32 s57, v251, 1
	s_add_i32 s18, s17, 0x2000
	v_readlane_b32 s58, v251, 2
	v_readlane_b32 s59, v251, 3
	s_mov_b64 s[20:21], s[56:57]
	s_add_u32 s1, s20, s12
	s_addc_u32 s5, s21, s13
	s_add_u32 s8, s2, 0x40000
	s_mov_b32 m0, s17
	s_addc_u32 s9, s3, 0
	s_add_i32 s19, s74, 0x14000
	global_load_lds_dwordx4 v164, s[2:3]
	s_mov_b32 m0, s18
	s_add_i32 s20, s19, s6
	global_load_lds_dwordx4 v166, s[2:3]
	s_mov_b32 m0, s20
	s_add_i32 s21, s20, 0x2000
	global_load_lds_dwordx4 v164, s[8:9]
	s_mov_b32 m0, s21
	s_mov_b64 s[22:23], s[58:59]
	global_load_lds_dwordx4 v166, s[8:9]
	s_add_u32 s8, s1, s7
	s_addc_u32 s9, s5, 0
	s_add_i32 s22, s74, s6
	s_add_i32 s23, s22, 0x2000
	s_mov_b32 m0, s22
	s_add_u32 s38, s8, 0x40000
	global_load_lds_dwordx4 v164, s[8:9]
	s_mov_b32 m0, s23
	s_addc_u32 s39, s9, 0
	s_add_i32 s24, s22, 0x4000
	global_load_lds_dwordx4 v166, s[8:9]
	s_mov_b32 m0, s24
	s_add_i32 s25, s22, 0x6000
	global_load_lds_dwordx4 v164, s[38:39]
	s_mov_b32 m0, s25
	v_mov_b32_e32 v165, v1
	global_load_lds_dwordx4 v166, s[38:39]
	v_mov_b32_e32 v167, v1
	v_lshl_add_u64 v[8:9], s[2:3], 0, v[164:165]
	v_lshl_add_u64 v[6:7], s[2:3], 0, v[166:167]
	v_lshl_add_u64 v[4:5], s[8:9], 0, v[164:165]
	s_cmp_lg_u32 s29, 1
	v_lshl_add_u64 v[2:3], s[8:9], 0, v[166:167]
	v_readlane_b32 s60, v251, 4
	v_readlane_b32 s61, v251, 5
	v_readlane_b32 s62, v251, 6
	v_readlane_b32 s63, v251, 7
	s_cbranch_scc1 .LBB0_503
	s_barrier
.LBB0_503:
	v_lshlrev_b32_e32 v10, 2, v131
	s_lshl_b32 s1, s29, 6
	v_lshl_or_b32 v0, v131, 6, v187
	s_lshl_b32 s29, s29, 13
	v_and_b32_e32 v10, 32, v10
	v_bitop3_b32 v11, v0, s29, v10 bitop3:0xde
	s_add_i32 s29, s74, 0x18000
	s_and_b32 s5, s36, 3
	s_add_i32 s36, s29, s6
	v_lshl_add_u64 v[8:9], v[8:9], 0, s[94:95]
	s_mov_b32 m0, s36
	s_add_i32 s37, s36, 0x2000
	s_add_i32 s38, s22, 0x8000
	s_add_i32 s39, s22, 0xa000
	s_waitcnt vmcnt(2)
	s_barrier
	global_load_lds_dwordx4 v[8:9], off
	v_lshl_add_u64 v[6:7], v[6:7], 0, s[94:95]
	s_mov_b32 m0, s37
	s_add_u32 s44, s2, 0x40080
	global_load_lds_dwordx4 v[6:7], off
	v_lshl_add_u64 v[4:5], v[4:5], 0, s[94:95]
	s_mov_b32 m0, s38
	s_addc_u32 s45, s3, 0
	s_add_i32 s42, s74, 0x1c000
	global_load_lds_dwordx4 v[4:5], off
	v_lshl_add_u64 v[2:3], v[2:3], 0, s[94:95]
	s_mov_b32 m0, s39
	s_add_i32 s43, s42, s6
	global_load_lds_dwordx4 v[2:3], off
	v_lshl_add_u64 v[2:3], s[44:45], 0, v[164:165]
	s_mov_b32 m0, s43
	v_readlane_b32 s56, v251, 0
	global_load_lds_dwordx4 v[2:3], off
	v_lshl_add_u64 v[2:3], s[44:45], 0, v[166:167]
	s_add_i32 s44, s43, 0x2000
	s_mov_b32 m0, s44
	s_add_u32 s6, s12, s7
	global_load_lds_dwordx4 v[2:3], off
	v_readlane_b32 s57, v251, 1
	s_addc_u32 s7, s13, 0
	v_readlane_b32 s58, v251, 2
	v_readlane_b32 s59, v251, 3
	s_mov_b64 s[48:49], s[56:57]
	v_lshlrev_b32_e32 v0, 14, v181
	s_add_u32 s45, s48, s6
	v_and_b32_e32 v0, 0xffff8000, v0
	s_addc_u32 s47, s49, s7
	v_lshl_add_u32 v0, v183, 11, v0
	v_and_b32_e32 v2, 1, v181
	v_readlane_b32 s12, v252, 20
	v_lshl_or_b32 v0, v2, 6, v0
	s_add_u32 s6, s12, s6
	v_readlane_b32 s12, v252, 21
	v_lshl_add_u32 v0, v184, 1, v0
	s_addc_u32 s7, s12, s7
	v_lshl_add_u64 v[2:3], s[6:7], 0, v[0:1]
	v_lshlrev_b32_e32 v0, 14, v182
	v_and_b32_e32 v0, 0xffff8000, v0
	v_lshl_add_u32 v0, v185, 11, v0
	v_and_b32_e32 v4, 1, v182
	v_lshl_or_b32 v0, v4, 6, v0
	v_lshl_add_u32 v0, v186, 1, v0
	v_lshl_add_u64 v[4:5], s[6:7], 0, v[0:1]
	s_add_u32 s6, s54, s10
	s_addc_u32 s7, s55, s11
	v_readlane_b32 s10, v253, 0
	v_readlane_b32 s11, v253, 1
	s_add_u32 s6, s10, s6
	s_waitcnt vmcnt(6)
	s_addc_u32 s7, s11, s7
	s_mov_b64 s[50:51], s[58:59]
	s_add_u32 s48, s6, 0x1d00100
	v_mov_b32_e32 v18, 0
	v_lshl_or_b32 v10, s5, 12, v188
	s_addc_u32 s49, s7, 0
	s_mov_b32 s50, -2
	s_mov_b64 s[6:7], 0
	v_add_u32_e32 v0, s74, v11
	v_lshl_add_u32 v0, s101, 12, v0
	v_mov_b32_e32 v19, v18
	v_mov_b32_e32 v20, v18
	v_mov_b32_e32 v21, v18
	s_waitcnt vmcnt(0)
	v_mov_b32_e32 v22, v18
	v_mov_b32_e32 v23, v18
	v_mov_b32_e32 v24, v18
	v_mov_b32_e32 v25, v18
	v_mov_b32_e32 v50, v18
	v_mov_b32_e32 v51, v18
	v_mov_b32_e32 v52, v18
	v_mov_b32_e32 v53, v18
	v_mov_b32_e32 v54, v18
	v_mov_b32_e32 v55, v18
	v_mov_b32_e32 v56, v18
	v_mov_b32_e32 v57, v18
	v_mov_b32_e32 v66, v18
	v_mov_b32_e32 v67, v18
	v_mov_b32_e32 v68, v18
	v_mov_b32_e32 v69, v18
	v_mov_b32_e32 v70, v18
	v_mov_b32_e32 v71, v18
	v_mov_b32_e32 v72, v18
	v_mov_b32_e32 v73, v18
	v_mov_b32_e32 v82, v18
	v_mov_b32_e32 v83, v18
	v_mov_b32_e32 v84, v18
	v_mov_b32_e32 v85, v18
	v_mov_b32_e32 v86, v18
	v_mov_b32_e32 v87, v18
	v_mov_b32_e32 v88, v18
	v_mov_b32_e32 v89, v18
	v_mov_b32_e32 v26, v18
	v_mov_b32_e32 v27, v18
	v_mov_b32_e32 v28, v18
	v_mov_b32_e32 v29, v18
	v_mov_b32_e32 v30, v18
	v_mov_b32_e32 v31, v18
	v_mov_b32_e32 v32, v18
	v_mov_b32_e32 v33, v18
	v_mov_b32_e32 v58, v18
	v_mov_b32_e32 v59, v18
	v_mov_b32_e32 v60, v18
	v_mov_b32_e32 v61, v18
	v_mov_b32_e32 v62, v18
	v_mov_b32_e32 v63, v18
	v_mov_b32_e32 v64, v18
	v_mov_b32_e32 v65, v18
	v_mov_b32_e32 v74, v18
	v_mov_b32_e32 v75, v18
	v_mov_b32_e32 v76, v18
	v_mov_b32_e32 v77, v18
	v_mov_b32_e32 v78, v18
	v_mov_b32_e32 v79, v18
	v_mov_b32_e32 v80, v18
	v_mov_b32_e32 v81, v18
	v_mov_b32_e32 v90, v18
	v_mov_b32_e32 v91, v18
	v_mov_b32_e32 v92, v18
	v_mov_b32_e32 v93, v18
	v_mov_b32_e32 v94, v18
	v_mov_b32_e32 v95, v18
	v_mov_b32_e32 v96, v18
	v_mov_b32_e32 v97, v18
	s_barrier
; #define PG8_STAGE(bufoff, gbase) do { _Pragma("unroll") for (int _i = 0; _i < 2; ++_i) \
;         __builtin_amdgcn_global_load_lds((const unsigned*)((const char*)(gbase) + voffA[_i]), (LAS unsigned*)(lds + (bufoff) + ldsw + _i * 8192), 16, 0, 0); } while (0)
; #define PG8_LDA(dst, b, h) do { _Pragma("unroll") for (int m = 0; m < 4; ++m) _Pragma("unroll") for (int k = 0; k < 2; ++k) dst[m][k] = *(const LAS h16x8*)(lds + PG8_SA(b, h) + aoff + m * 2048 + k * 1024); } while (0)
; #define PG8_LDB(dst, b, h) do { _Pragma("unroll") for (int n = 0; n < 2; ++n) _Pragma("unroll") for (int k = 0; k < 2; ++k) dst[n][k] = *(const LAS h16x8*)(lds + PG8_SB(b, h) + boff + n * 2048 + k * 1024); } while (0)
; #define PG8_LDA1(dst, b) do { if constexpr (!HALFM) PG8_LDA(dst, b, 1); } while (0)
; #define PG8_MMA1(At, B0, B1) do { if constexpr (!HALFM) { PG8_MMA(1, 0, At, B0); PG8_MMA(1, 1, At, B1); } } while (0)
; #define PG8_WAIT_V(n) asm volatile("s_waitcnt vmcnt(" #n ")" ::: "memory")
; #define PG8_BAR __builtin_amdgcn_s_barrier()
; template <class Epi, bool ALIGN_EPI, bool SP2, bool BF = false, bool HALFM = false, class Order = StaticOrder>
; __device__ __forceinline__ void gemm_phase(LAS unsigned char* lds, const int tid, const Gemm g, const Order& S, const Epi& E, const bool dry = false) {
;     ...
;             PG8_LDB(B0, 0, 0); PG8_LDB(B1, 0, 1); PG8_SCHED; PG8_LDA(At, 0, 0); PG8_STAGE(PG8_SA(1, 1), a1 + hstep);
;             PG8_WAIT_V(8); PG8_WAIT_L(0); PG8_BAR; PG8_MMA(0, 0, At, B0); PG8_MMA(0, 1, At, B1); PG8_BAR; PG8_SCHED;
;             PG8_LDA1(At, 0); PG8_STAGE(PG8_SB(0, 0), b2); PG8_STAGE(PG8_SB(0, 1), b2 + hstep); PG8_STAGE(PG8_SA(0, 0), a2);
;             PG8_WAIT_V(8); PG8_WAIT_L(0); PG8_BAR; PG8_MMA1(At, B0, B1); PG8_BAR; PG8_SCHED;
;             PG8_LDB(B0, 1, 0); PG8_LDB(B1, 1, 1); PG8_SCHED; PG8_LDA(At, 1, 0); PG8_STAGE(PG8_SA(0, 1), a2 + hstep);
;             PG8_WAIT_V(8); PG8_WAIT_L(0); PG8_BAR; PG8_MMA(0, 0, At, B0); PG8_MMA(0, 1, At, B1); PG8_BAR; PG8_SCHED;
;             PG8_LDA1(At, 1); PG8_STAGE(PG8_SB(1, 0), b3); PG8_STAGE(PG8_SB(1, 1), b3 + hstep); PG8_STAGE(PG8_SA(1, 0), a3);
;             PG8_WAIT_V(8); PG8_WAIT_L(0); PG8_BAR; PG8_MMA1(At, B0, B1); PG8_BAR; PG8_SCHED;
;     ...
;         if constexpr (ALIGN_EPI) { if (wr == 0) PG8_BAR; }
;         if (!dry) { int fr2 = fr, fq2 = fq; asm volatile("" : "+v"(fr2), "+v"(fq2)); E(acc, cur, wr, wc, fr2, fq2); }
	v_readlane_b32 s60, v251, 4
	v_readlane_b32 s61, v251, 5
	v_readlane_b32 s62, v251, 6
	v_readlane_b32 s63, v251, 7
.LBB0_504:
	v_add_u32_e32 v11, s16, v10
	ds_read_b128 v[6:9], v11
	ds_read_b128 v[12:15], v11 offset:1024
	ds_read_b128 v[34:37], v11 offset:2048
	ds_read_b128 v[38:41], v11 offset:3072
	v_add_u32_e32 v11, s19, v10
	s_add_u32 s10, s45, s6
	ds_read_b128 v[42:45], v11
	ds_read_b128 v[46:49], v11 offset:1024
	ds_read_b128 v[98:101], v11 offset:2048
	ds_read_b128 v[102:105], v11 offset:3072
	s_addc_u32 s11, s47, s7
	s_add_u32 s10, s10, 0x100
	s_addc_u32 s11, s11, 0
	s_add_u32 s51, s48, s6
	s_addc_u32 s52, s49, s7
	s_cmpk_eq_i32 s6, 0x700
	s_cselect_b32 s13, s9, s11
	s_cselect_b32 s12, s8, s10
	s_cselect_b32 s11, s3, s52
	s_cselect_b32 s10, s2, s51
	v_lshl_add_u64 v[16:17], v[2:3], 0, s[6:7]
	s_add_i32 m0, s22, 0xc000
	ds_read_b128 v[106:109], v0
	ds_read_b128 v[110:113], v0 offset:1024
	ds_read_b128 v[114:117], v0 offset:2048
	ds_read_b128 v[118:121], v0 offset:3072
	s_nop 0
	s_nop 0
	s_nop 0
	s_nop 0
	global_load_lds_dwordx4 v[16:17], off
	v_lshl_add_u64 v[16:17], v[4:5], 0, s[6:7]
	s_add_i32 m0, s22, 0xe000
	s_nop 0
	global_load_lds_dwordx4 v[16:17], off
	s_waitcnt vmcnt(8)
	s_waitcnt lgkmcnt(0)
	s_barrier
	s_waitcnt lgkmcnt(0)
	v_mfma_f32_16x16x32_f16 v[94:97], v[6:9], v[106:109], v[94:97]
	v_mfma_f32_16x16x32_f16 v[90:93], v[34:37], v[106:109], v[90:93]
	v_mfma_f32_16x16x32_f16 v[78:81], v[6:9], v[114:117], v[78:81]
	v_mfma_f32_16x16x32_f16 v[74:77], v[34:37], v[114:117], v[74:77]
	v_mfma_f32_16x16x32_f16 v[94:97], v[12:15], v[110:113], v[94:97]
	v_mfma_f32_16x16x32_f16 v[90:93], v[38:41], v[110:113], v[90:93]
	v_mfma_f32_16x16x32_f16 v[78:81], v[12:15], v[118:121], v[78:81]
	v_mfma_f32_16x16x32_f16 v[74:77], v[38:41], v[118:121], v[74:77]
	v_mfma_f32_16x16x32_f16 v[26:29], v[42:45], v[106:109], v[86:89]
	v_mfma_f32_16x16x32_f16 v[34:37], v[46:49], v[110:113], v[26:29]
	v_mfma_f32_16x16x32_f16 v[26:29], v[98:101], v[106:109], v[82:85]
	v_mfma_f32_16x16x32_f16 v[38:41], v[102:105], v[110:113], v[26:29]
	v_mfma_f32_16x16x32_f16 v[26:29], v[42:45], v[114:117], v[70:73]
	v_mfma_f32_16x16x32_f16 v[70:73], v[46:49], v[118:121], v[26:29]
	v_mfma_f32_16x16x32_f16 v[26:29], v[98:101], v[114:117], v[66:69]
	v_mfma_f32_16x16x32_f16 v[66:69], v[102:105], v[118:121], v[26:29]
	s_barrier
	s_mov_b32 m0, s17
	v_lshl_add_u64 v[144:145], s[10:11], 0, v[164:165]
	s_add_u32 s52, s10, 0x40000
	global_load_lds_dwordx4 v[144:145], off
	v_lshl_add_u64 v[146:147], s[10:11], 0, v[166:167]
	s_mov_b32 m0, s18
	s_addc_u32 s53, s11, 0
	global_load_lds_dwordx4 v[146:147], off
	v_lshl_add_u64 v[20:21], s[52:53], 0, v[164:165]
	s_mov_b32 m0, s20
	v_lshl_add_u64 v[148:149], s[12:13], 0, v[164:165]
	global_load_lds_dwordx4 v[20:21], off
	v_lshl_add_u64 v[20:21], s[52:53], 0, v[166:167]
	s_mov_b32 m0, s21
	v_lshl_add_u64 v[150:151], s[12:13], 0, v[166:167]
	global_load_lds_dwordx4 v[20:21], off
	s_mov_b32 m0, s22
	s_nop 0
	global_load_lds_dwordx4 v[148:149], off
	s_mov_b32 m0, s23
	s_nop 0
	global_load_lds_dwordx4 v[150:151], off
	s_waitcnt vmcnt(8)
	s_waitcnt lgkmcnt(0)
	s_barrier
	s_barrier
	v_add_u32_e32 v11, s29, v10
	ds_read_b128 v[26:29], v11
	ds_read_b128 v[30:33], v11 offset:1024
	ds_read_b128 v[42:45], v11 offset:2048
	ds_read_b128 v[46:49], v11 offset:3072
	v_add_u32_e32 v11, s42, v10
	ds_read_b128 v[98:101], v11
	ds_read_b128 v[102:105], v11 offset:1024
	ds_read_b128 v[106:109], v11 offset:2048
	ds_read_b128 v[110:113], v11 offset:3072
	s_add_u32 s12, s12, 0x40000
	s_addc_u32 s13, s13, 0
	s_mov_b32 m0, s24
	v_lshl_add_u64 v[20:21], s[12:13], 0, v[164:165]
	ds_read_b128 v[82:85], v0 offset:32768
	ds_read_b128 v[114:117], v0 offset:33792
	ds_read_b128 v[118:121], v0 offset:34816
	ds_read_b128 v[122:125], v0 offset:35840
	s_nop 0
	s_nop 0
	s_nop 0
	s_nop 0
	global_load_lds_dwordx4 v[20:21], off
	v_lshl_add_u64 v[20:21], s[12:13], 0, v[166:167]
	s_mov_b32 m0, s25
	s_nop 0
	global_load_lds_dwordx4 v[20:21], off
	s_waitcnt vmcnt(8)
	s_waitcnt lgkmcnt(0)
	s_barrier
	s_waitcnt lgkmcnt(0)
	v_mfma_f32_16x16x32_f16 v[86:89], v[26:29], v[82:85], v[94:97]
	v_mfma_f32_16x16x32_f16 v[78:81], v[26:29], v[118:121], v[78:81]
	v_mfma_f32_16x16x32_f16 v[94:97], v[30:33], v[114:117], v[86:89]
	v_mfma_f32_16x16x32_f16 v[86:89], v[42:45], v[82:85], v[90:93]
	v_mfma_f32_16x16x32_f16 v[78:81], v[30:33], v[122:125], v[78:81]
	v_mfma_f32_16x16x32_f16 v[74:77], v[42:45], v[118:121], v[74:77]
	v_mfma_f32_16x16x32_f16 v[90:93], v[46:49], v[114:117], v[86:89]
	v_mfma_f32_16x16x32_f16 v[74:77], v[46:49], v[122:125], v[74:77]
	v_mfma_f32_16x16x32_f16 v[6:9], v[98:101], v[82:85], v[34:37]
	v_mfma_f32_16x16x32_f16 v[86:89], v[102:105], v[114:117], v[6:9]
	v_mfma_f32_16x16x32_f16 v[6:9], v[106:109], v[82:85], v[38:41]
	v_mfma_f32_16x16x32_f16 v[82:85], v[110:113], v[114:117], v[6:9]
	v_mfma_f32_16x16x32_f16 v[6:9], v[98:101], v[118:121], v[70:73]
	v_mfma_f32_16x16x32_f16 v[70:73], v[102:105], v[122:125], v[6:9]
	v_mfma_f32_16x16x32_f16 v[6:9], v[106:109], v[118:121], v[66:69]
	v_mfma_f32_16x16x32_f16 v[66:69], v[110:113], v[122:125], v[6:9]
	s_barrier
	s_mov_b32 m0, s36
	s_nop 3
	v_lshl_add_u64 v[6:7], v[144:145], 0, s[94:95]
	s_add_u32 s10, s10, 0x40080
	global_load_lds_dwordx4 v[6:7], off
	v_lshl_add_u64 v[6:7], v[146:147], 0, s[94:95]
	s_mov_b32 m0, s37
	s_addc_u32 s11, s11, 0
	global_load_lds_dwordx4 v[6:7], off
	v_lshl_add_u64 v[6:7], s[10:11], 0, v[164:165]
	s_mov_b32 m0, s43
	s_nop 0
	global_load_lds_dwordx4 v[6:7], off
	v_lshl_add_u64 v[6:7], s[10:11], 0, v[166:167]
	s_mov_b32 m0, s44
	s_nop 0
	global_load_lds_dwordx4 v[6:7], off
	v_lshl_add_u64 v[6:7], v[148:149], 0, s[94:95]
	s_mov_b32 m0, s38
	s_nop 0
	global_load_lds_dwordx4 v[6:7], off
	v_lshl_add_u64 v[6:7], v[150:151], 0, s[94:95]
	s_mov_b32 m0, s39
	s_nop 0
	global_load_lds_dwordx4 v[6:7], off
	s_waitcnt vmcnt(8)
	s_waitcnt lgkmcnt(0)
	s_barrier
	s_barrier
	s_add_i32 s50, s50, 2
	s_add_u32 s6, s6, 0x100
	s_addc_u32 s7, s7, 0
	s_cmp_gt_u32 s50, 13
	s_cbranch_scc0 .LBB0_504
	s_cmpk_lt_u32 s15, 0x100
	s_mov_b64 s[60:61], 0x800
	s_cbranch_scc0 .LBB0_507
	s_barrier

;     __device__ __forceinline__ void operator()(const f32x4 (&acc)[2][2][4][2], const pg8::Unit& u, int wr, int wc, int fr, int fq) const {
;     ...
;         const unsigned rqo = (unsigned)WS_ROWSQ + ((unsigned)(u.pn * 4 + wc) * (unsigned)MROWS + (unsigned)u.pm * 256u + rloc) * 4u;
;         const bool odd = (fr & 1) != 0;
;         const unsigned eoA = (((unsigned)u.pm * 256u + hmo + (unsigned)(wr * 64 + (fr & ~1))) * D + u.pn * 256 + wc * 64) * 2u + (odd ? 64u : 0u) + 16u * fq;
; #pragma unroll
;         for (int ai = 0; ai < 2; ++ai)
; #pragma unroll
;             for (int m = 0; m < 4; ++m) { if (half && ai == 1) continue; const unsigned rr = (unsigned)(ai * 128 + m * 16); const unsigned o = eoA + rr * (D * 2u); float ss = 0.f;
;                 const u32x4 la = *(const GAS u32x4*)((const GAS char*)ws + (unsigned)WS_X16 + o), lb = *(const GAS u32x4*)((const GAS char*)ws + (unsigned)WS_X16 + o + D * 2u);
;                 u32x4 xr[2];
; #pragma unroll
;                 for (int c = 0; c < 4; ++c) { const unsigned pa = (unsigned)__builtin_amdgcn_update_dpp(0, (int)la[c], 0xB1, 0xF, 0xF, false), pb = (unsigned)__builtin_amdgcn_update_dpp(0, (int)lb[c], 0xB1, 0xF, 0xF, false);
;                     xr[0][c] = odd ? pb : la[c]; xr[1][c] = odd ? lb[c] : pa; }
;                 u32x4 w[2], v[2];
; #pragma unroll
;                 for (int bj = 0; bj < 2; ++bj) { const h16x8 xb = __builtin_bit_cast(h16x8, xr[bj]);
;                     const f32x4 x0 = (f32x4){(float)xb[0], (float)xb[1], (float)xb[2], (float)xb[3]} + g4[bj][0] * acc[ai][bj][m][0], x1 = (f32x4){(float)xb[4], (float)xb[5], (float)xb[6], (float)xb[7]} + g4[bj][1] * acc[ai][bj][m][1];
;                     ss += ((x0[0] * x0[0] + x0[1] * x0[1]) + (x0[2] * x0[2] + x0[3] * x0[3])) + ((x1[0] * x1[0] + x1[1] * x1[1]) + (x1[2] * x1[2] + x1[3] * x1[3]));
;                     w[bj].x = cvtpk_h(x0[0], x0[1]); w[bj].y = cvtpk_h(x0[2], x0[3]); w[bj].z = cvtpk_h(x1[0], x1[1]); w[bj].w = cvtpk_h(x1[2], x1[3]);
;                     const f32x4 y0 = x0 * a4[bj][0], y1 = x1 * a4[bj][1]; v[bj].x = cvtpk_h(y0[0], y0[1]); v[bj].y = cvtpk_h(y0[2], y0[3]); v[bj].z = cvtpk_h(y1[0], y1[1]); v[bj].w = cvtpk_h(y1[2], y1[3]); }
;                 stg_line_pair(ws, (unsigned)WS_X16 + o, D * 2u, w[0], w[1], odd);
;                 if (an_off) stg_line_pair(ws, (unsigned)WS_XS + o, D * 2u, v[0], v[1], odd);
.LBB0_515:
	s_lshl_b32 s8, s14, 7
	s_lshl_b32 vcc_lo, s101, 5
	s_add_i32 s8, s8, vcc_lo
	s_lshl_b32 s0, s0, 8
	s_add_i32 s10, s1, s8
	v_and_b32_e32 v0, 0x1ffffe, v131
	s_add_i32 s10, s10, s0
	v_add_u32_e32 v0, s10, v0
	v_lshl_add_u32 v0, v0, 10, s12
	v_and_b32_e32 v106, 1, v131
	v_or_b32_e32 v0, s11, v0
	v_lshlrev_b32_e32 v0, 1, v0
	v_lshlrev_b32_e32 v98, 6, v106
	v_lshlrev_b32_e32 v99, 4, v180
	s_add_u32 s8, s6, 0x16f80000
	v_add3_u32 v0, v98, v99, v0
	s_addc_u32 s9, s7, 0
	global_load_dwordx4 v[98:101], v0, s[8:9]
	global_load_dwordx4 v[102:105], v0, s[8:9] offset:2048
	v_mov_b32_e32 v107, v1
	v_mov_b32_e32 v108, v1
	v_mov_b32_e32 v109, v1
	v_mov_b32_e32 v111, v1
	v_mov_b32_e32 v113, v1
	v_mov_b32_e32 v114, v1
	v_mov_b32_e32 v110, v1
	v_mov_b32_e32 v112, v1
	v_cmp_eq_u32_e64 s[0:1], 0, v106
	v_mov_b32_e32 v115, v1
	v_mov_b32_e32 v117, v1
	v_mov_b32_e32 v119, v1
	v_mov_b32_e32 v121, v1
	v_mov_b32_e32 v116, v1
	v_mov_b32_e32 v118, v1
	v_mov_b32_e32 v120, v1
	v_mov_b32_e32 v122, v1
	v_add_u32_e32 v123, 0x16f80000, v0
	s_and_b64 vcc, exec, s[2:3]
	s_waitcnt vmcnt(0)
	v_mov_b32_dpp v107, v98 quad_perm:[1,0,3,2] row_mask:0xf bank_mask:0xf
	v_mov_b32_dpp v108, v102 quad_perm:[1,0,3,2] row_mask:0xf bank_mask:0xf
	v_mov_b32_dpp v109, v99 quad_perm:[1,0,3,2] row_mask:0xf bank_mask:0xf
	v_mov_b32_dpp v111, v100 quad_perm:[1,0,3,2] row_mask:0xf bank_mask:0xf
	v_mov_b32_dpp v113, v101 quad_perm:[1,0,3,2] row_mask:0xf bank_mask:0xf
	v_mov_b32_dpp v114, v105 quad_perm:[1,0,3,2] row_mask:0xf bank_mask:0xf
	v_mov_b32_dpp v110, v103 quad_perm:[1,0,3,2] row_mask:0xf bank_mask:0xf
	v_mov_b32_dpp v112, v104 quad_perm:[1,0,3,2] row_mask:0xf bank_mask:0xf
	v_cndmask_b32_e64 v106, v108, v98, s[0:1]
	v_cndmask_b32_e64 v107, v102, v107, s[0:1]
	v_cndmask_b32_e64 v109, v103, v109, s[0:1]
	v_cndmask_b32_e64 v111, v104, v111, s[0:1]
	v_cndmask_b32_e64 v108, v114, v101, s[0:1]
	v_cndmask_b32_e64 v113, v105, v113, s[0:1]
	v_cndmask_b32_e64 v102, v110, v99, s[0:1]
	v_cndmask_b32_e64 v103, v112, v100, s[0:1]
	v_cvt_f32_f16_e32 v98, v106
	v_cvt_f32_f16_sdwa v99, v106 dst_sel:DWORD dst_unused:UNUSED_PAD src0_sel:WORD_1
	v_cvt_f32_f16_e32 v104, v108
	v_cvt_f32_f16_sdwa v105, v108 dst_sel:DWORD dst_unused:UNUSED_PAD src0_sel:WORD_1
	v_cvt_f32_f16_e32 v106, v107
	v_cvt_f32_f16_sdwa v107, v107 dst_sel:DWORD dst_unused:UNUSED_PAD src0_sel:WORD_1
	v_cvt_f32_f16_e32 v108, v109
	v_cvt_f32_f16_sdwa v109, v109 dst_sel:DWORD dst_unused:UNUSED_PAD src0_sel:WORD_1
	v_cvt_f32_f16_e32 v110, v111
	v_cvt_f32_f16_sdwa v111, v111 dst_sel:DWORD dst_unused:UNUSED_PAD src0_sel:WORD_1
	v_cvt_f32_f16_e32 v112, v113
	v_cvt_f32_f16_sdwa v113, v113 dst_sel:DWORD dst_unused:UNUSED_PAD src0_sel:WORD_1
	v_cvt_f32_f16_e32 v100, v102
	v_cvt_f32_f16_sdwa v101, v102 dst_sel:DWORD dst_unused:UNUSED_PAD src0_sel:WORD_1
	v_cvt_f32_f16_e32 v102, v103
	v_cvt_f32_f16_sdwa v103, v103 dst_sel:DWORD dst_unused:UNUSED_PAD src0_sel:WORD_1
	v_pk_fma_f32 v[88:89], v[88:89], v[44:45], v[108:109]
	v_pk_fma_f32 v[86:87], v[86:87], v[42:43], v[106:107]
	v_pk_fma_f32 v[84:85], v[84:85], v[48:49], v[112:113]
	v_pk_fma_f32 v[82:83], v[82:83], v[46:47], v[110:111]
	v_pk_fma_f32 v[96:97], v[96:97], v[36:37], v[100:101]
	v_pk_fma_f32 v[94:95], v[94:95], v[34:35], v[98:99]
	v_pk_fma_f32 v[92:93], v[92:93], v[40:41], v[104:105]
	v_pk_fma_f32 v[90:91], v[90:91], v[38:39], v[102:103]
	v_cvt_pk_f16_f32 v102, v86, v87
	v_cvt_pk_f16_f32 v103, v88, v89
	v_cvt_pk_f16_f32 v104, v82, v83
	v_cvt_pk_f16_f32 v105, v84, v85
	v_cvt_pk_f16_f32 v98, v94, v95
	v_cvt_pk_f16_f32 v99, v96, v97
	v_cvt_pk_f16_f32 v100, v90, v91
	v_cvt_pk_f16_f32 v101, v92, v93
	v_mov_b32_dpp v115, v102 quad_perm:[1,0,3,2] row_mask:0xf bank_mask:0xf
	v_mov_b32_dpp v117, v103 quad_perm:[1,0,3,2] row_mask:0xf bank_mask:0xf
	v_mov_b32_dpp v119, v104 quad_perm:[1,0,3,2] row_mask:0xf bank_mask:0xf
	v_mov_b32_dpp v121, v105 quad_perm:[1,0,3,2] row_mask:0xf bank_mask:0xf
	v_mov_b32_dpp v116, v98 quad_perm:[1,0,3,2] row_mask:0xf bank_mask:0xf
	v_mov_b32_dpp v118, v99 quad_perm:[1,0,3,2] row_mask:0xf bank_mask:0xf
	v_mov_b32_dpp v120, v100 quad_perm:[1,0,3,2] row_mask:0xf bank_mask:0xf
	v_mov_b32_dpp v122, v101 quad_perm:[1,0,3,2] row_mask:0xf bank_mask:0xf
	v_cndmask_b32_e64 v98, v115, v98, s[0:1]
	v_cndmask_b32_e64 v99, v117, v99, s[0:1]
	v_cndmask_b32_e64 v100, v119, v100, s[0:1]
	v_cndmask_b32_e64 v101, v121, v101, s[0:1]
	v_cndmask_b32_e64 v102, v102, v116, s[0:1]
	v_cndmask_b32_e64 v103, v103, v118, s[0:1]
	v_cndmask_b32_e64 v104, v104, v120, s[0:1]
	v_cndmask_b32_e64 v105, v105, v122, s[0:1]
	global_store_dwordx4 v123, v[98:101], s[6:7]
	s_nop 1
	v_add_u32_e32 v98, 0x16f80800, v0
	global_store_dwordx4 v98, v[102:105], s[6:7]
	s_cbranch_vccnz .LBB0_517
	v_pk_mul_f32 v[98:99], v[16:17], v[84:85]
	v_pk_mul_f32 v[100:101], v[14:15], v[82:83]
	v_cvt_pk_f16_f32 v105, v98, v99
	v_cvt_pk_f16_f32 v104, v100, v101
	v_pk_mul_f32 v[98:99], v[12:13], v[88:89]
	v_pk_mul_f32 v[100:101], v[10:11], v[86:87]
	v_cvt_pk_f16_f32 v103, v98, v99
	v_cvt_pk_f16_f32 v102, v100, v101
	v_pk_mul_f32 v[98:99], v[8:9], v[92:93]
	v_pk_mul_f32 v[100:101], v[6:7], v[90:91]
	v_cvt_pk_f16_f32 v106, v98, v99
	v_cvt_pk_f16_f32 v107, v100, v101
	v_pk_mul_f32 v[98:99], v[4:5], v[96:97]
	v_pk_mul_f32 v[100:101], v[2:3], v[94:95]
	v_cvt_pk_f16_f32 v99, v98, v99
	v_cvt_pk_f16_f32 v98, v100, v101
	v_mov_b32_e32 v101, v1
	v_mov_b32_e32 v100, v1
	v_add_u32_e32 v108, 0x3d80000, v0
	v_mov_b32_dpp v101, v98 quad_perm:[1,0,3,2] row_mask:0xf bank_mask:0xf
	v_mov_b32_dpp v100, v102 quad_perm:[1,0,3,2] row_mask:0xf bank_mask:0xf
	v_cndmask_b32_e64 v102, v102, v101, s[0:1]
	v_mov_b32_e32 v101, v1
	v_cndmask_b32_e64 v98, v100, v98, s[0:1]
	v_mov_b32_e32 v100, v1
	v_mov_b32_dpp v101, v99 quad_perm:[1,0,3,2] row_mask:0xf bank_mask:0xf
	s_nop 0
	v_mov_b32_dpp v100, v103 quad_perm:[1,0,3,2] row_mask:0xf bank_mask:0xf
	v_cndmask_b32_e64 v103, v103, v101, s[0:1]
	v_mov_b32_e32 v101, v1
	v_cndmask_b32_e64 v99, v100, v99, s[0:1]
	v_mov_b32_e32 v100, v1
	v_mov_b32_dpp v101, v107 quad_perm:[1,0,3,2] row_mask:0xf bank_mask:0xf
	s_nop 0
	v_mov_b32_dpp v100, v104 quad_perm:[1,0,3,2] row_mask:0xf bank_mask:0xf
	v_cndmask_b32_e64 v104, v104, v101, s[0:1]
	v_mov_b32_e32 v101, v1
	v_cndmask_b32_e64 v100, v100, v107, s[0:1]
	v_mov_b32_e32 v107, v1
	v_mov_b32_dpp v101, v105 quad_perm:[1,0,3,2] row_mask:0xf bank_mask:0xf
	v_cndmask_b32_e64 v101, v101, v106, s[0:1]
	v_mov_b32_dpp v107, v106 quad_perm:[1,0,3,2] row_mask:0xf bank_mask:0xf
	v_cndmask_b32_e64 v105, v105, v107, s[0:1]
	global_store_dwordx4 v108, v[98:101], s[6:7]
	s_nop 1
	v_add_u32_e32 v98, 0x3d80800, v0
	global_store_dwordx4 v98, v[102:105], s[6:7]

; #define GAS __attribute__((address_space(1)))
; __device__ __forceinline__ unsigned cvtpk_h(float lo, float hi) { f32x2 v = {lo, hi}; h16x2 b = __builtin_convertvector(v, h16x2); return __builtin_bit_cast(unsigned, b); }
;     __device__ __forceinline__ void operator()(const f32x4 (&acc)[2][2][4][2], const pg8::Unit& u, int wr, int wc, int fr, int fq) const {
;     ...
;             for (int m = 0; m < 4; ++m) { if (half && ai == 1) continue; const unsigned rr = (unsigned)(ai * 128 + m * 16); const unsigned o = eoA + rr * (D * 2u); float ss = 0.f;
;                 const u32x4 la = *(const GAS u32x4*)((const GAS char*)ws + (unsigned)WS_X16 + o), lb = *(const GAS u32x4*)((const GAS char*)ws + (unsigned)WS_X16 + o + D * 2u);
;                 u32x4 xr[2];
; #pragma unroll
;                 for (int c = 0; c < 4; ++c) { const unsigned pa = (unsigned)__builtin_amdgcn_update_dpp(0, (int)la[c], 0xB1, 0xF, 0xF, false), pb = (unsigned)__builtin_amdgcn_update_dpp(0, (int)lb[c], 0xB1, 0xF, 0xF, false);
;                     xr[0][c] = odd ? pb : la[c]; xr[1][c] = odd ? lb[c] : pa; }
;                 u32x4 w[2], v[2];
; #pragma unroll
;                 for (int bj = 0; bj < 2; ++bj) { const h16x8 xb = __builtin_bit_cast(h16x8, xr[bj]);
;                     const f32x4 x0 = (f32x4){(float)xb[0], (float)xb[1], (float)xb[2], (float)xb[3]} + g4[bj][0] * acc[ai][bj][m][0], x1 = (f32x4){(float)xb[4], (float)xb[5], (float)xb[6], (float)xb[7]} + g4[bj][1] * acc[ai][bj][m][1];
;                     ss += ((x0[0] * x0[0] + x0[1] * x0[1]) + (x0[2] * x0[2] + x0[3] * x0[3])) + ((x1[0] * x1[0] + x1[1] * x1[1]) + (x1[2] * x1[2] + x1[3] * x1[3]));
;                     w[bj].x = cvtpk_h(x0[0], x0[1]); w[bj].y = cvtpk_h(x0[2], x0[3]); w[bj].z = cvtpk_h(x1[0], x1[1]); w[bj].w = cvtpk_h(x1[2], x1[3]);
;                     const f32x4 y0 = x0 * a4[bj][0], y1 = x1 * a4[bj][1]; v[bj].x = cvtpk_h(y0[0], y0[1]); v[bj].y = cvtpk_h(y0[2], y0[3]); v[bj].z = cvtpk_h(y1[0], y1[1]); v[bj].w = cvtpk_h(y1[2], y1[3]); }
;                 stg_line_pair(ws, (unsigned)WS_X16 + o, D * 2u, w[0], w[1], odd);
;                 if (an_off) stg_line_pair(ws, (unsigned)WS_XS + o, D * 2u, v[0], v[1], odd);
;                 ss = red4(ss, fq * 16 + fr); if (fq == 0) stg_f1(ws, rqo + rr * 4u, ss);
.LBB0_523:
	s_or_b64 exec, exec, s[10:11]
	s_branch .LBB0_531
	v_add_u32_e32 v70, 0x10000, v0
	global_load_dwordx4 v[66:69], v70, s[8:9]
	s_nop 0
	global_load_dwordx4 v[70:73], v70, s[8:9] offset:2048
	v_mov_b32_e32 v74, v1
	v_mov_b32_e32 v75, v1
	v_add_u32_e32 v78, 0x16f90000, v0
	s_and_b64 vcc, exec, s[2:3]
	s_waitcnt vmcnt(0)
	v_mov_b32_dpp v74, v66 quad_perm:[1,0,3,2] row_mask:0xf bank_mask:0xf
	v_mov_b32_dpp v75, v70 quad_perm:[1,0,3,2] row_mask:0xf bank_mask:0xf
	v_cndmask_b32_e64 v75, v75, v66, s[0:1]
	v_cndmask_b32_e64 v70, v70, v74, s[0:1]
	v_mov_b32_e32 v66, v1
	v_mov_b32_e32 v74, v1
	s_nop 0
	v_mov_b32_dpp v66, v67 quad_perm:[1,0,3,2] row_mask:0xf bank_mask:0xf
	v_mov_b32_dpp v74, v71 quad_perm:[1,0,3,2] row_mask:0xf bank_mask:0xf
	v_cndmask_b32_e64 v74, v74, v67, s[0:1]
	v_cndmask_b32_e64 v71, v71, v66, s[0:1]
	v_mov_b32_e32 v66, v1
	v_mov_b32_e32 v67, v1
	s_nop 0
	v_mov_b32_dpp v66, v68 quad_perm:[1,0,3,2] row_mask:0xf bank_mask:0xf
	v_mov_b32_dpp v67, v72 quad_perm:[1,0,3,2] row_mask:0xf bank_mask:0xf
	v_cndmask_b32_e64 v76, v67, v68, s[0:1]
	v_cndmask_b32_e64 v72, v72, v66, s[0:1]
	v_mov_b32_e32 v66, v1
	v_mov_b32_e32 v67, v1
	v_cvt_f32_f16_e32 v68, v74
	v_mov_b32_dpp v66, v69 quad_perm:[1,0,3,2] row_mask:0xf bank_mask:0xf
	v_mov_b32_dpp v67, v73 quad_perm:[1,0,3,2] row_mask:0xf bank_mask:0xf
	v_cndmask_b32_e64 v77, v67, v69, s[0:1]
	v_cndmask_b32_e64 v73, v73, v66, s[0:1]
	v_cvt_f32_f16_e32 v66, v75
	v_cvt_f32_f16_sdwa v67, v75 dst_sel:DWORD dst_unused:UNUSED_PAD src0_sel:WORD_1
	v_cvt_f32_f16_sdwa v69, v74 dst_sel:DWORD dst_unused:UNUSED_PAD src0_sel:WORD_1
	v_pk_fma_f32 v[62:63], v[62:63], v[34:35], v[66:67]
	v_cvt_f32_f16_e32 v66, v76
	v_cvt_f32_f16_sdwa v67, v76 dst_sel:DWORD dst_unused:UNUSED_PAD src0_sel:WORD_1
	v_pk_fma_f32 v[64:65], v[64:65], v[36:37], v[68:69]
	v_cvt_f32_f16_e32 v68, v77
	v_cvt_f32_f16_sdwa v69, v77 dst_sel:DWORD dst_unused:UNUSED_PAD src0_sel:WORD_1
	v_pk_fma_f32 v[58:59], v[58:59], v[38:39], v[66:67]
	v_cvt_f32_f16_e32 v66, v70
	v_cvt_f32_f16_sdwa v67, v70 dst_sel:DWORD dst_unused:UNUSED_PAD src0_sel:WORD_1
	v_pk_fma_f32 v[60:61], v[60:61], v[40:41], v[68:69]
	v_cvt_f32_f16_e32 v68, v71
	v_cvt_f32_f16_sdwa v69, v71 dst_sel:DWORD dst_unused:UNUSED_PAD src0_sel:WORD_1
	v_pk_fma_f32 v[54:55], v[54:55], v[42:43], v[66:67]
	v_cvt_f32_f16_e32 v66, v72
	v_cvt_f32_f16_sdwa v67, v72 dst_sel:DWORD dst_unused:UNUSED_PAD src0_sel:WORD_1
	v_pk_fma_f32 v[56:57], v[56:57], v[44:45], v[68:69]
	v_cvt_f32_f16_e32 v68, v73
	v_cvt_f32_f16_sdwa v69, v73 dst_sel:DWORD dst_unused:UNUSED_PAD src0_sel:WORD_1
	v_cvt_pk_f16_f32 v74, v62, v63
	v_mov_b32_e32 v70, v1
	v_cvt_pk_f16_f32 v75, v64, v65
	v_pk_fma_f32 v[50:51], v[50:51], v[46:47], v[66:67]
	v_cvt_pk_f16_f32 v67, v54, v55
	v_mov_b32_e32 v66, v1
	v_mov_b32_dpp v70, v74 quad_perm:[1,0,3,2] row_mask:0xf bank_mask:0xf
	v_mov_b32_e32 v71, v1
	v_cvt_pk_f16_f32 v76, v58, v59
	v_pk_fma_f32 v[52:53], v[52:53], v[48:49], v[68:69]
	v_cvt_pk_f16_f32 v68, v56, v57
	v_mov_b32_dpp v66, v67 quad_perm:[1,0,3,2] row_mask:0xf bank_mask:0xf
	v_cndmask_b32_e64 v70, v67, v70, s[0:1]
	v_mov_b32_e32 v67, v1
	v_mov_b32_dpp v71, v75 quad_perm:[1,0,3,2] row_mask:0xf bank_mask:0xf
	v_mov_b32_e32 v72, v1
	v_cvt_pk_f16_f32 v69, v50, v51
	v_mov_b32_dpp v67, v68 quad_perm:[1,0,3,2] row_mask:0xf bank_mask:0xf
	v_cndmask_b32_e64 v71, v68, v71, s[0:1]
	v_mov_b32_e32 v68, v1
	v_mov_b32_dpp v72, v76 quad_perm:[1,0,3,2] row_mask:0xf bank_mask:0xf
	v_cvt_pk_f16_f32 v73, v52, v53
	v_mov_b32_dpp v68, v69 quad_perm:[1,0,3,2] row_mask:0xf bank_mask:0xf
	v_cndmask_b32_e64 v72, v69, v72, s[0:1]
	v_mov_b32_e32 v69, v1
	v_cvt_pk_f16_f32 v77, v60, v61
	v_cndmask_b32_e64 v66, v66, v74, s[0:1]
	v_mov_b32_dpp v69, v73 quad_perm:[1,0,3,2] row_mask:0xf bank_mask:0xf
	v_mov_b32_e32 v74, v1
	v_cndmask_b32_e64 v67, v67, v75, s[0:1]
	v_cndmask_b32_e64 v68, v68, v76, s[0:1]
	v_mov_b32_dpp v74, v77 quad_perm:[1,0,3,2] row_mask:0xf bank_mask:0xf
	v_cndmask_b32_e64 v69, v69, v77, s[0:1]
	v_cndmask_b32_e64 v73, v73, v74, s[0:1]
	global_store_dwordx4 v78, v[66:69], s[6:7]
	s_nop 1
	v_add_u32_e32 v66, 0x16f90800, v0
	global_store_dwordx4 v66, v[70:73], s[6:7]
	s_cbranch_vccnz .LBB0_525
	v_pk_mul_f32 v[66:67], v[16:17], v[52:53]
	v_pk_mul_f32 v[68:69], v[14:15], v[50:51]
	v_cvt_pk_f16_f32 v73, v66, v67
	v_cvt_pk_f16_f32 v72, v68, v69
	v_pk_mul_f32 v[66:67], v[12:13], v[56:57]
	v_pk_mul_f32 v[68:69], v[10:11], v[54:55]
	v_cvt_pk_f16_f32 v71, v66, v67
	v_cvt_pk_f16_f32 v70, v68, v69
	v_pk_mul_f32 v[66:67], v[8:9], v[60:61]
	v_pk_mul_f32 v[68:69], v[6:7], v[58:59]
	v_cvt_pk_f16_f32 v74, v66, v67
	v_cvt_pk_f16_f32 v75, v68, v69
	v_pk_mul_f32 v[66:67], v[4:5], v[64:65]
	v_pk_mul_f32 v[68:69], v[2:3], v[62:63]
	v_cvt_pk_f16_f32 v67, v66, v67
	v_cvt_pk_f16_f32 v66, v68, v69
	v_mov_b32_e32 v69, v1
	v_mov_b32_e32 v68, v1
	v_add_u32_e32 v76, 0x3d90000, v0
	v_mov_b32_dpp v69, v66 quad_perm:[1,0,3,2] row_mask:0xf bank_mask:0xf
	v_mov_b32_dpp v68, v70 quad_perm:[1,0,3,2] row_mask:0xf bank_mask:0xf
	v_cndmask_b32_e64 v70, v70, v69, s[0:1]
	v_mov_b32_e32 v69, v1
	v_cndmask_b32_e64 v66, v68, v66, s[0:1]
	v_mov_b32_e32 v68, v1
	v_mov_b32_dpp v69, v67 quad_perm:[1,0,3,2] row_mask:0xf bank_mask:0xf
	s_nop 0
	v_mov_b32_dpp v68, v71 quad_perm:[1,0,3,2] row_mask:0xf bank_mask:0xf
	v_cndmask_b32_e64 v71, v71, v69, s[0:1]
	v_mov_b32_e32 v69, v1
	v_cndmask_b32_e64 v67, v68, v67, s[0:1]
	v_mov_b32_e32 v68, v1
	v_mov_b32_dpp v69, v75 quad_perm:[1,0,3,2] row_mask:0xf bank_mask:0xf
	s_nop 0
	v_mov_b32_dpp v68, v72 quad_perm:[1,0,3,2] row_mask:0xf bank_mask:0xf
	v_cndmask_b32_e64 v72, v72, v69, s[0:1]
	v_mov_b32_e32 v69, v1
	v_cndmask_b32_e64 v68, v68, v75, s[0:1]
	v_mov_b32_e32 v75, v1
	v_mov_b32_dpp v69, v73 quad_perm:[1,0,3,2] row_mask:0xf bank_mask:0xf
	v_cndmask_b32_e64 v69, v69, v74, s[0:1]
	v_mov_b32_dpp v75, v74 quad_perm:[1,0,3,2] row_mask:0xf bank_mask:0xf
	v_cndmask_b32_e64 v73, v73, v75, s[0:1]
	global_store_dwordx4 v76, v[66:69], s[6:7]
	s_nop 1
	v_add_u32_e32 v66, 0x3d90800, v0
	global_store_dwordx4 v66, v[70:73], s[6:7]
